# scan no longer loads the all-zero upper-triangular 16x16 blocks of the intra-chunk score image (lanes exec-masked on the rp loads)
# speedup vs baseline: 1.0014x; 1.0014x over previous
; __device__ __forceinline__ int tid_of(int wave_id) { int t = wave_id * 64 + lane_id(); asm volatile("" : "+v"(t)); return t; }
; __device__ __forceinline__ void hgrn_scan(const Params& p, LAS unsigned char* lds, int chain) {
;     int tid_o = tid_of(p.wave_id);
;     const int tid = tid_o, lane = tid & 63, wave = __builtin_amdgcn_readfirstlane(tid >> 6);
;     const int li = lane & 15, g = lane >> 4, qq = li >> 2, pp = li & 3;
;     const int dir = chain / (BATCH * NHEAD), b = (chain / NHEAD) % BATCH, h = chain % NHEAD;
;     const bf16* IA = (const bf16*)(p.ws + WS_IA) + h * HD;
;     bf16* O = (bf16*)(p.ws + (dir == 0 ? WS_OF2 : WS_OB2)) + h * HD + 16 * wave + 4 * g;
;     const long ost = dir ? -(long)WA : (long)WA;
;     const unsigned char* img0 = p.ws + WS_HIMG + (size_t)chain * NCH * HIMG_BYTES;
;     f32x4 S[8];
; #pragma unroll
;     for (int i = 0; i < 8; ++i) S[i] = (f32x4){0.f, 0.f, 0.f, 0.f};
;     u32x4 rq[2][2], rk[2][2], rp[2], rd[2], rv[2][2];
.LBB0_397:
	s_mul_i32 s23, s2, 0x16c800
	s_mul_hi_i32 s22, s2, 0x16c800
	s_waitcnt lgkmcnt(0)
	s_add_u32 s3, s26, s23
	s_addc_u32 s5, s27, s22
	s_add_u32 s12, s3, 0x14342000
	s_barrier
	s_waitcnt vmcnt(4)
	v_mbcnt_lo_u32_b32 v0, -1, 0
	v_mbcnt_hi_u32_b32 v0, -1, v0
	s_addc_u32 s13, s5, 0
	v_add_u32_e32 v47, s76, v0
	v_bfe_u32 v235, v47, 1, 2
	v_lshrrev_b32_e32 v236, 7, v47
	v_cmp_le_u32_e64 s[100:101], v235, v236
	s_add_u32 s4, s3, 0x14346000
	v_lshlrev_b32_e32 v40, 4, v47
	s_addc_u32 s5, s5, 0
	v_ashrrev_i32_e32 v41, 31, v40
	v_add_u32_e32 v42, 0x2000, v40
	v_lshl_add_u64 v[0:1], s[4:5], 0, v[40:41]
	v_ashrrev_i32_e32 v43, 31, v42
	v_lshl_add_u64 v[2:3], s[4:5], 0, v[42:43]
	global_load_dwordx4 v[16:19], v[0:1], off
	global_load_dwordx4 v[20:23], v[2:3], off
	v_readfirstlane_b32 s20, v47
	v_cmp_gt_i32_e64 s[4:5], 32, v47
	v_lshl_add_u64 v[44:45], s[12:13], 0, v[40:41]
	s_and_saveexec_b64 s[6:7], s[4:5]
	s_cbranch_execz .LBB0_399
	v_add_co_u32_e32 v0, vcc, 0xa000, v44
	s_nop 1
	v_addc_co_u32_e32 v1, vcc, 0, v45, vcc
	global_load_dwordx4 v[0:3], v[0:1], off

.LBB0_414:
	v_add_u32_e32 v96, 0x2200, v160
	s_waitcnt vmcnt(3)
	ds_write2_b64 v160, v[8:9], v[10:11] offset1:1
	s_waitcnt vmcnt(2)
	ds_write2_b64 v96, v[12:13], v[14:15] offset1:1
	s_and_saveexec_b64 s[18:19], s[4:5]
	v_add_u32_e32 v96, 0x1d200, v134
	ds_write_b128 v96, v[4:7]
	s_or_b64 exec, exec, s[18:19]
	v_add_u32_e32 v96, v152, v112
	s_waitcnt vmcnt(0)
	ds_write_b128 v96, v[28:31]
	v_add_u32_e32 v96, v152, v136
	s_cmp_gt_u32 s23, 32
	ds_write_b128 v96, v[24:27]
	s_cbranch_scc1 .LBB0_422
	s_cmp_eq_u32 s14, 0
	s_cbranch_scc1 .LBB0_419
	v_lshl_add_u64 v[8:9], v[128:129], 0, s[14:15]
	v_add_co_u32_e32 v12, vcc, 0x14360000, v8
	v_lshl_add_u64 v[10:11], v[130:131], 0, s[14:15]
	s_nop 0
	v_addc_co_u32_e32 v13, vcc, 0, v9, vcc
	v_add_co_u32_e32 v10, vcc, 0x14360000, v10
	s_nop 1
	v_addc_co_u32_e32 v11, vcc, 0, v11, vcc
	v_add_co_u32_e32 v8, vcc, 0x14368000, v8
	global_load_dwordx4 v[40:43], v[12:13], off offset:1536
	global_load_dwordx4 v[44:47], v[10:11], off offset:1536
	v_addc_co_u32_e32 v9, vcc, 0, v9, vcc
	s_and_saveexec_b64 s[18:19], s[100:101]
	global_load_dwordx4 v[56:59], v[8:9], off offset:1536
	s_mov_b64 exec, s[18:19]

.LBB0_432:
	s_cmp_gt_u32 s12, 32
	s_cbranch_scc1 .LBB0_407
	s_waitcnt vmcnt(1)
	v_lshl_add_u64 v[32:33], v[128:129], 0, s[14:15]
	v_add_co_u32_e32 v16, vcc, 0x1436a000, v32
	v_lshl_add_u64 v[20:21], v[130:131], 0, s[14:15]
	s_nop 0
	v_addc_co_u32_e32 v17, vcc, 0, v33, vcc
	v_add_co_u32_e32 v18, vcc, 0x1436a000, v20
	s_nop 1
	v_addc_co_u32_e32 v19, vcc, 0, v21, vcc
	global_load_dwordx4 v[48:51], v[16:17], off offset:2048
	global_load_dwordx4 v[52:55], v[18:19], off offset:2048
	v_add_co_u32_e32 v16, vcc, 0x14372000, v32
	s_nop 1
	v_addc_co_u32_e32 v17, vcc, 0, v33, vcc
	v_add_co_u32_e32 v18, vcc, 0x1436e000, v32
	s_nop 1
	v_addc_co_u32_e32 v19, vcc, 0, v33, vcc
	v_add_co_u32_e32 v20, vcc, 0x1436e000, v20
	s_and_saveexec_b64 s[16:17], s[100:101]
	global_load_dwordx4 v[60:63], v[16:17], off offset:2048
	s_mov_b64 exec, s[16:17]
	s_nop 0
	global_load_dwordx4 v[16:19], v[18:19], off offset:2048
	v_addc_co_u32_e32 v21, vcc, 0, v21, vcc
	global_load_dwordx4 v[20:23], v[20:21], off offset:2048
	s_and_saveexec_b64 s[16:17], s[4:5]
	s_cbranch_execz .LBB0_406
	v_add_co_u32_e32 v0, vcc, 0x14374000, v32
	s_nop 1
	v_addc_co_u32_e32 v1, vcc, 0, v33, vcc
	global_load_dwordx4 v[0:3], v[0:1], off offset:2048
	s_branch .LBB0_406
